# P8 k-loop: LDS operand reads software-pipelined into the MFMA segments (second X register set), per-phase counted vmcnt waits
# speedup vs baseline: 1.0091x; 1.0072x over previous
.Lp8_nostage:
	v_add_u32_e32 v168, 0x18000, v236
	v_add_u32_e32 v169, 0x1c000, v236
	ds_read_b128 v[130:133], v240
	ds_read_b128 v[134:137], v240 offset:1024
	ds_read_b128 v[138:141], v240 offset:2048
	ds_read_b128 v[142:145], v240 offset:3072
	ds_read_b128 v[146:149], v241
	ds_read_b128 v[150:153], v241 offset:1024
	ds_read_b128 v[154:157], v241 offset:2048
	ds_read_b128 v[158:161], v241 offset:3072
	ds_read_b128 v[176:179], v241 offset:4096
	ds_read_b128 v[180:183], v241 offset:5120
	ds_read_b128 v[184:187], v241 offset:6144
	ds_read_b128 v[188:191], v241 offset:7168
	s_add_u32 s50, s48, 0xfff80080
	s_addc_u32 s51, s49, -1
	s_cmp_eq_u32 s80, s87
	s_cselect_b32 s53, s41, s51
	s_cselect_b32 s52, s47, s50
	s_cselect_b32 s51, s39, s75
	s_cselect_b32 s50, s73, s74
	s_add_i32 m0, s21, 0xc000
	s_nop 0
	global_load_lds_dwordx4 v166, s[48:49]
	s_add_i32 m0, s21, 0xe000
	s_nop 0
	global_load_lds_dwordx4 v170, s[48:49]
	s_waitcnt vmcnt(10)
	s_barrier
	s_waitcnt lgkmcnt(0)
	s_setprio 1
	v_mfma_f32_16x16x32_bf16 v[126:129], v[130:133], v[146:149], 0
	ds_read_b128 v[192:195], v242
	v_mfma_f32_16x16x32_bf16 v[122:125], v[138:141], v[146:149], 0
	v_mfma_f32_16x16x32_bf16 v[118:121], v[130:133], v[154:157], 0
	v_mfma_f32_16x16x32_bf16 v[114:117], v[138:141], v[154:157], 0
	v_mfma_f32_16x16x32_bf16 v[106:109], v[130:133], v[176:179], 0
	ds_read_b128 v[196:199], v242 offset:1024
	v_mfma_f32_16x16x32_bf16 v[98:101], v[138:141], v[176:179], 0
	v_mfma_f32_16x16x32_bf16 v[90:93], v[130:133], v[184:187], 0
	v_mfma_f32_16x16x32_bf16 v[82:85], v[138:141], v[184:187], 0
	v_mfma_f32_16x16x32_bf16 v[126:129], v[134:137], v[150:153], v[126:129]
	ds_read_b128 v[200:203], v242 offset:2048
	v_mfma_f32_16x16x32_bf16 v[122:125], v[142:145], v[150:153], v[122:125]
	v_mfma_f32_16x16x32_bf16 v[118:121], v[134:137], v[158:161], v[118:121]
	v_mfma_f32_16x16x32_bf16 v[114:117], v[142:145], v[158:161], v[114:117]
	v_mfma_f32_16x16x32_bf16 v[106:109], v[134:137], v[180:183], v[106:109]
	ds_read_b128 v[204:207], v242 offset:3072
	v_mfma_f32_16x16x32_bf16 v[98:101], v[142:145], v[180:183], v[98:101]
	v_mfma_f32_16x16x32_bf16 v[90:93], v[134:137], v[188:191], v[90:93]
	v_mfma_f32_16x16x32_bf16 v[82:85], v[142:145], v[188:191], v[82:85]
	s_setprio 0
	s_barrier
	s_add_i32 s81, s68, s56
	s_add_u32 s96, s50, 0x80
	s_addc_u32 s97, s51, 0
	s_mov_b32 m0, s81
	s_nop 0
	global_load_lds_dwordx4 v162, s[50:51]
	s_add_i32 m0, s81, 0x2000
	s_nop 0
	global_load_lds_dwordx4 v164, s[50:51]
	s_waitcnt vmcnt(10)
	s_barrier
	s_waitcnt lgkmcnt(0)
	s_setprio 1
	v_mfma_f32_16x16x32_bf16 v[110:113], v[192:195], v[146:149], 0
	ds_read_b128 v[208:211], v241 offset:16384
	v_mfma_f32_16x16x32_bf16 v[102:105], v[200:203], v[146:149], 0
	v_mfma_f32_16x16x32_bf16 v[94:97], v[192:195], v[154:157], 0
	ds_read_b128 v[212:215], v241 offset:17408
	v_mfma_f32_16x16x32_bf16 v[86:89], v[200:203], v[154:157], 0
	v_mfma_f32_16x16x32_bf16 v[78:81], v[192:195], v[176:179], 0
	ds_read_b128 v[216:219], v241 offset:18432
	v_mfma_f32_16x16x32_bf16 v[74:77], v[200:203], v[176:179], 0
	v_mfma_f32_16x16x32_bf16 v[70:73], v[192:195], v[184:187], 0
	ds_read_b128 v[220:223], v241 offset:19456
	v_mfma_f32_16x16x32_bf16 v[66:69], v[200:203], v[184:187], 0
	v_mfma_f32_16x16x32_bf16 v[110:113], v[196:199], v[150:153], v[110:113]
	ds_read_b128 v[224:227], v241 offset:20480
	v_mfma_f32_16x16x32_bf16 v[102:105], v[204:207], v[150:153], v[102:105]
	v_mfma_f32_16x16x32_bf16 v[94:97], v[196:199], v[158:161], v[94:97]
	ds_read_b128 v[228:231], v241 offset:21504
	v_mfma_f32_16x16x32_bf16 v[86:89], v[204:207], v[158:161], v[86:89]
	v_mfma_f32_16x16x32_bf16 v[78:81], v[196:199], v[180:183], v[78:81]
	ds_read_b128 v[232:235], v241 offset:22528
	v_mfma_f32_16x16x32_bf16 v[74:77], v[204:207], v[180:183], v[74:77]
	v_mfma_f32_16x16x32_bf16 v[70:73], v[196:199], v[188:191], v[70:73]
	ds_read_b128 v[246:249], v241 offset:23552
	v_mfma_f32_16x16x32_bf16 v[66:69], v[204:207], v[188:191], v[66:69]
	s_setprio 0
	s_barrier
	s_mov_b32 m0, s21
	s_add_u32 s94, s52, 0x80
	s_addc_u32 s95, s53, 0
	global_load_lds_dwordx4 v162, s[52:53]
	s_mov_b32 m0, s59
	s_nop 0
	global_load_lds_dwordx4 v164, s[52:53]
	s_waitcnt vmcnt(8)
	s_barrier
	s_waitcnt lgkmcnt(0)
	s_setprio 1
	v_mfma_f32_16x16x32_bf16 v[62:65], v[130:133], v[208:211], 0
	ds_read_b128 v[146:149], v241 offset:32768
	v_mfma_f32_16x16x32_bf16 v[58:61], v[138:141], v[208:211], 0
	v_mfma_f32_16x16x32_bf16 v[54:57], v[130:133], v[216:219], 0
	ds_read_b128 v[150:153], v241 offset:33792
	v_mfma_f32_16x16x32_bf16 v[50:53], v[138:141], v[216:219], 0
	v_mfma_f32_16x16x32_bf16 v[42:45], v[130:133], v[224:227], 0
	ds_read_b128 v[154:157], v241 offset:34816
	v_mfma_f32_16x16x32_bf16 v[34:37], v[138:141], v[224:227], 0
	v_mfma_f32_16x16x32_bf16 v[26:29], v[130:133], v[232:235], 0
	ds_read_b128 v[158:161], v241 offset:35840
	v_mfma_f32_16x16x32_bf16 v[18:21], v[138:141], v[232:235], 0
	v_mfma_f32_16x16x32_bf16 v[62:65], v[134:137], v[212:215], v[62:65]
	ds_read_b128 v[176:179], v241 offset:36864
	v_mfma_f32_16x16x32_bf16 v[58:61], v[142:145], v[212:215], v[58:61]
	v_mfma_f32_16x16x32_bf16 v[54:57], v[134:137], v[220:223], v[54:57]
	ds_read_b128 v[180:183], v241 offset:37888
	v_mfma_f32_16x16x32_bf16 v[50:53], v[142:145], v[220:223], v[50:53]
	v_mfma_f32_16x16x32_bf16 v[42:45], v[134:137], v[228:231], v[42:45]
	ds_read_b128 v[184:187], v241 offset:38912
	v_mfma_f32_16x16x32_bf16 v[34:37], v[142:145], v[228:231], v[34:37]
	v_mfma_f32_16x16x32_bf16 v[26:29], v[134:137], v[246:249], v[26:29]
	ds_read_b128 v[188:191], v241 offset:39936
	v_mfma_f32_16x16x32_bf16 v[18:21], v[142:145], v[246:249], v[18:21]
	s_setprio 0
	s_barrier
	s_add_u32 s82, s50, 0x80000
	s_addc_u32 s83, s51, 0
	s_add_i32 s81, s69, s56
	s_mov_b32 m0, s81
	s_nop 0
	global_load_lds_dwordx4 v162, s[82:83]
	s_add_i32 m0, s81, 0x2000
	s_nop 0
	global_load_lds_dwordx4 v164, s[82:83]
	s_waitcnt vmcnt(10)
	s_barrier
	s_waitcnt lgkmcnt(0)
	s_setprio 1
	v_mfma_f32_16x16x32_bf16 v[46:49], v[192:195], v[208:211], 0
	ds_read_b128 v[130:133], v168
	v_mfma_f32_16x16x32_bf16 v[38:41], v[200:203], v[208:211], 0
	v_mfma_f32_16x16x32_bf16 v[30:33], v[192:195], v[216:219], 0
	v_mfma_f32_16x16x32_bf16 v[22:25], v[200:203], v[216:219], 0
	v_mfma_f32_16x16x32_bf16 v[14:17], v[192:195], v[224:227], 0
	ds_read_b128 v[134:137], v168 offset:1024
	v_mfma_f32_16x16x32_bf16 v[10:13], v[200:203], v[224:227], 0
	v_mfma_f32_16x16x32_bf16 v[6:9], v[192:195], v[232:235], 0
	v_mfma_f32_16x16x32_bf16 v[2:5], v[200:203], v[232:235], 0
	v_mfma_f32_16x16x32_bf16 v[46:49], v[196:199], v[212:215], v[46:49]
	ds_read_b128 v[138:141], v168 offset:2048
	v_mfma_f32_16x16x32_bf16 v[38:41], v[204:207], v[212:215], v[38:41]
	v_mfma_f32_16x16x32_bf16 v[30:33], v[196:199], v[220:223], v[30:33]
	v_mfma_f32_16x16x32_bf16 v[22:25], v[204:207], v[220:223], v[22:25]
	v_mfma_f32_16x16x32_bf16 v[14:17], v[196:199], v[228:231], v[14:17]
	ds_read_b128 v[142:145], v168 offset:3072
	v_mfma_f32_16x16x32_bf16 v[10:13], v[204:207], v[228:231], v[10:13]
	v_mfma_f32_16x16x32_bf16 v[6:9], v[196:199], v[246:249], v[6:9]
	v_mfma_f32_16x16x32_bf16 v[2:5], v[204:207], v[246:249], v[2:5]
	s_setprio 0
	s_barrier
	s_add_i32 s81, 0, 0x18000
	s_add_u32 s52, s52, 0x80000
	s_addc_u32 s53, s53, 0
	s_mov_b32 m0, s60
	s_nop 0
	global_load_lds_dwordx4 v162, s[52:53]
	s_mov_b32 m0, s61
	s_nop 0
	global_load_lds_dwordx4 v164, s[52:53]
	s_waitcnt vmcnt(10)
	s_barrier
	s_waitcnt lgkmcnt(0)
	s_setprio 1
	v_mfma_f32_16x16x32_bf16 v[126:129], v[130:133], v[146:149], v[126:129]
	ds_read_b128 v[192:195], v169
	v_mfma_f32_16x16x32_bf16 v[122:125], v[138:141], v[146:149], v[122:125]
	v_mfma_f32_16x16x32_bf16 v[118:121], v[130:133], v[154:157], v[118:121]
	v_mfma_f32_16x16x32_bf16 v[114:117], v[138:141], v[154:157], v[114:117]
	v_mfma_f32_16x16x32_bf16 v[106:109], v[130:133], v[176:179], v[106:109]
	ds_read_b128 v[196:199], v169 offset:1024
	v_mfma_f32_16x16x32_bf16 v[98:101], v[138:141], v[176:179], v[98:101]
	v_mfma_f32_16x16x32_bf16 v[90:93], v[130:133], v[184:187], v[90:93]
	v_mfma_f32_16x16x32_bf16 v[82:85], v[138:141], v[184:187], v[82:85]
	v_mfma_f32_16x16x32_bf16 v[126:129], v[134:137], v[150:153], v[126:129]
	ds_read_b128 v[200:203], v169 offset:2048
	v_mfma_f32_16x16x32_bf16 v[122:125], v[142:145], v[150:153], v[122:125]
	v_mfma_f32_16x16x32_bf16 v[118:121], v[134:137], v[158:161], v[118:121]
	v_mfma_f32_16x16x32_bf16 v[114:117], v[142:145], v[158:161], v[114:117]
	v_mfma_f32_16x16x32_bf16 v[106:109], v[134:137], v[180:183], v[106:109]
	ds_read_b128 v[204:207], v169 offset:3072
	v_mfma_f32_16x16x32_bf16 v[98:101], v[142:145], v[180:183], v[98:101]
	v_mfma_f32_16x16x32_bf16 v[90:93], v[134:137], v[188:191], v[90:93]
	v_mfma_f32_16x16x32_bf16 v[82:85], v[142:145], v[188:191], v[82:85]
	s_setprio 0
	s_barrier
	s_add_i32 s52, 0, 0x1c000
	s_add_i32 s53, s81, s56
	s_mov_b32 m0, s53
	s_nop 0
	global_load_lds_dwordx4 v162, s[96:97]
	s_add_i32 m0, s53, 0x2000
	s_nop 0
	global_load_lds_dwordx4 v164, s[96:97]
	s_waitcnt vmcnt(10)
	s_barrier
	s_waitcnt lgkmcnt(0)
	s_setprio 1
	v_mfma_f32_16x16x32_bf16 v[110:113], v[192:195], v[146:149], v[110:113]
	ds_read_b128 v[208:211], v241 offset:49152
	v_mfma_f32_16x16x32_bf16 v[102:105], v[200:203], v[146:149], v[102:105]
	v_mfma_f32_16x16x32_bf16 v[94:97], v[192:195], v[154:157], v[94:97]
	ds_read_b128 v[212:215], v241 offset:50176
	v_mfma_f32_16x16x32_bf16 v[86:89], v[200:203], v[154:157], v[86:89]
	v_mfma_f32_16x16x32_bf16 v[78:81], v[192:195], v[176:179], v[78:81]
	ds_read_b128 v[216:219], v241 offset:51200
	v_mfma_f32_16x16x32_bf16 v[74:77], v[200:203], v[176:179], v[74:77]
	v_mfma_f32_16x16x32_bf16 v[70:73], v[192:195], v[184:187], v[70:73]
	ds_read_b128 v[220:223], v241 offset:52224
	v_mfma_f32_16x16x32_bf16 v[66:69], v[200:203], v[184:187], v[66:69]
	v_mfma_f32_16x16x32_bf16 v[110:113], v[196:199], v[150:153], v[110:113]
	ds_read_b128 v[224:227], v241 offset:53248
	v_mfma_f32_16x16x32_bf16 v[102:105], v[204:207], v[150:153], v[102:105]
	v_mfma_f32_16x16x32_bf16 v[94:97], v[196:199], v[158:161], v[94:97]
	ds_read_b128 v[228:231], v241 offset:54272
	v_mfma_f32_16x16x32_bf16 v[86:89], v[204:207], v[158:161], v[86:89]
	v_mfma_f32_16x16x32_bf16 v[78:81], v[196:199], v[180:183], v[78:81]
	ds_read_b128 v[232:235], v241 offset:55296
	v_mfma_f32_16x16x32_bf16 v[74:77], v[204:207], v[180:183], v[74:77]
	v_mfma_f32_16x16x32_bf16 v[70:73], v[196:199], v[188:191], v[70:73]
	ds_read_b128 v[246:249], v241 offset:56320
	v_mfma_f32_16x16x32_bf16 v[66:69], v[204:207], v[188:191], v[66:69]
	s_setprio 0
	s_barrier
	s_mov_b32 m0, s64
	s_nop 0
	global_load_lds_dwordx4 v162, s[94:95]
	s_mov_b32 m0, s65
	s_nop 0
	global_load_lds_dwordx4 v164, s[94:95]
	s_waitcnt vmcnt(8)
	s_barrier
	s_waitcnt lgkmcnt(0)
	s_setprio 1
	v_mfma_f32_16x16x32_bf16 v[62:65], v[130:133], v[208:211], v[62:65]
	ds_read_b128 v[146:149], v241
	v_mfma_f32_16x16x32_bf16 v[58:61], v[138:141], v[208:211], v[58:61]
	v_mfma_f32_16x16x32_bf16 v[54:57], v[130:133], v[216:219], v[54:57]
	ds_read_b128 v[150:153], v241 offset:1024
	v_mfma_f32_16x16x32_bf16 v[50:53], v[138:141], v[216:219], v[50:53]
	v_mfma_f32_16x16x32_bf16 v[42:45], v[130:133], v[224:227], v[42:45]
	ds_read_b128 v[154:157], v241 offset:2048
	v_mfma_f32_16x16x32_bf16 v[34:37], v[138:141], v[224:227], v[34:37]
	v_mfma_f32_16x16x32_bf16 v[26:29], v[130:133], v[232:235], v[26:29]
	ds_read_b128 v[158:161], v241 offset:3072
	v_mfma_f32_16x16x32_bf16 v[18:21], v[138:141], v[232:235], v[18:21]
	v_mfma_f32_16x16x32_bf16 v[62:65], v[134:137], v[212:215], v[62:65]
	ds_read_b128 v[176:179], v241 offset:4096
	v_mfma_f32_16x16x32_bf16 v[58:61], v[142:145], v[212:215], v[58:61]
	v_mfma_f32_16x16x32_bf16 v[54:57], v[134:137], v[220:223], v[54:57]
	ds_read_b128 v[180:183], v241 offset:5120
	v_mfma_f32_16x16x32_bf16 v[50:53], v[142:145], v[220:223], v[50:53]
	v_mfma_f32_16x16x32_bf16 v[42:45], v[134:137], v[228:231], v[42:45]
	ds_read_b128 v[184:187], v241 offset:6144
	v_mfma_f32_16x16x32_bf16 v[34:37], v[142:145], v[228:231], v[34:37]
	v_mfma_f32_16x16x32_bf16 v[26:29], v[134:137], v[246:249], v[26:29]
	ds_read_b128 v[188:191], v241 offset:7168
	v_mfma_f32_16x16x32_bf16 v[18:21], v[142:145], v[246:249], v[18:21]
	s_setprio 0
	s_barrier
	s_add_u32 s50, s50, 0x80080
	s_addc_u32 s51, s51, 0
	s_add_i32 s52, s52, s56
	s_mov_b32 m0, s52
	s_nop 0
	global_load_lds_dwordx4 v162, s[50:51]
	s_add_i32 m0, s52, 0x2000
	s_nop 0
	global_load_lds_dwordx4 v164, s[50:51]
	s_waitcnt vmcnt(10)
	s_barrier
	s_waitcnt lgkmcnt(0)
	s_setprio 1
	v_mfma_f32_16x16x32_bf16 v[46:49], v[192:195], v[208:211], v[46:49]
	ds_read_b128 v[130:133], v240
	v_mfma_f32_16x16x32_bf16 v[38:41], v[200:203], v[208:211], v[38:41]
	v_mfma_f32_16x16x32_bf16 v[30:33], v[192:195], v[216:219], v[30:33]
	v_mfma_f32_16x16x32_bf16 v[22:25], v[200:203], v[216:219], v[22:25]
	v_mfma_f32_16x16x32_bf16 v[14:17], v[192:195], v[224:227], v[14:17]
	ds_read_b128 v[134:137], v240 offset:1024
	v_mfma_f32_16x16x32_bf16 v[10:13], v[200:203], v[224:227], v[10:13]
	v_mfma_f32_16x16x32_bf16 v[6:9], v[192:195], v[232:235], v[6:9]
	v_mfma_f32_16x16x32_bf16 v[2:5], v[200:203], v[232:235], v[2:5]
	v_mfma_f32_16x16x32_bf16 v[46:49], v[196:199], v[212:215], v[46:49]
	ds_read_b128 v[138:141], v240 offset:2048
	v_mfma_f32_16x16x32_bf16 v[38:41], v[204:207], v[212:215], v[38:41]
	v_mfma_f32_16x16x32_bf16 v[30:33], v[196:199], v[220:223], v[30:33]
	v_mfma_f32_16x16x32_bf16 v[22:25], v[204:207], v[220:223], v[22:25]
	v_mfma_f32_16x16x32_bf16 v[14:17], v[196:199], v[228:231], v[14:17]
	ds_read_b128 v[142:145], v240 offset:3072
	v_mfma_f32_16x16x32_bf16 v[10:13], v[204:207], v[228:231], v[10:13]
	v_mfma_f32_16x16x32_bf16 v[6:9], v[196:199], v[246:249], v[6:9]
	v_mfma_f32_16x16x32_bf16 v[2:5], v[204:207], v[246:249], v[2:5]
	s_setprio 0
	s_add_i32 s80, s80, 2
	s_add_u32 s48, s48, 0x100
	s_addc_u32 s49, s49, 0
	s_add_u32 s74, s74, 0x100
	s_addc_u32 s75, s75, 0
	s_cmp_gt_u32 s80, s87
	s_barrier
	s_cbranch_scc0 .LBB0_1098
	s_branch .Lp8_loop_exit
.LBB0_1098:
	s_add_u32 s50, s48, 0xfff80080
	s_addc_u32 s51, s49, -1
	s_cmp_eq_u32 s80, s87
	s_cselect_b32 s53, s41, s51
	s_cselect_b32 s52, s47, s50
	s_cselect_b32 s51, s39, s75
	s_cselect_b32 s50, s73, s74
	s_add_i32 m0, s21, 0xc000
	s_nop 0
	global_load_lds_dwordx4 v166, s[48:49]
	s_add_i32 m0, s21, 0xe000
	s_nop 0
	global_load_lds_dwordx4 v170, s[48:49]
	s_waitcnt vmcnt(10)
	s_barrier
	s_waitcnt lgkmcnt(0)
	s_setprio 1
	v_mfma_f32_16x16x32_bf16 v[126:129], v[130:133], v[146:149], v[126:129]
	ds_read_b128 v[192:195], v242
	v_mfma_f32_16x16x32_bf16 v[122:125], v[138:141], v[146:149], v[122:125]
	v_mfma_f32_16x16x32_bf16 v[118:121], v[130:133], v[154:157], v[118:121]
	v_mfma_f32_16x16x32_bf16 v[114:117], v[138:141], v[154:157], v[114:117]
	v_mfma_f32_16x16x32_bf16 v[106:109], v[130:133], v[176:179], v[106:109]
	ds_read_b128 v[196:199], v242 offset:1024
	v_mfma_f32_16x16x32_bf16 v[98:101], v[138:141], v[176:179], v[98:101]
	v_mfma_f32_16x16x32_bf16 v[90:93], v[130:133], v[184:187], v[90:93]
	v_mfma_f32_16x16x32_bf16 v[82:85], v[138:141], v[184:187], v[82:85]
	v_mfma_f32_16x16x32_bf16 v[126:129], v[134:137], v[150:153], v[126:129]
	ds_read_b128 v[200:203], v242 offset:2048
	v_mfma_f32_16x16x32_bf16 v[122:125], v[142:145], v[150:153], v[122:125]
	v_mfma_f32_16x16x32_bf16 v[118:121], v[134:137], v[158:161], v[118:121]
	v_mfma_f32_16x16x32_bf16 v[114:117], v[142:145], v[158:161], v[114:117]
	v_mfma_f32_16x16x32_bf16 v[106:109], v[134:137], v[180:183], v[106:109]
	ds_read_b128 v[204:207], v242 offset:3072
	v_mfma_f32_16x16x32_bf16 v[98:101], v[142:145], v[180:183], v[98:101]
	v_mfma_f32_16x16x32_bf16 v[90:93], v[134:137], v[188:191], v[90:93]
	v_mfma_f32_16x16x32_bf16 v[82:85], v[142:145], v[188:191], v[82:85]
	s_setprio 0
	s_barrier
	s_add_i32 s81, s68, s56
	s_add_u32 s96, s50, 0x80
	s_addc_u32 s97, s51, 0
	s_mov_b32 m0, s81
	s_nop 0
	global_load_lds_dwordx4 v162, s[50:51]
	s_add_i32 m0, s81, 0x2000
	s_nop 0
	global_load_lds_dwordx4 v164, s[50:51]
	s_waitcnt vmcnt(10)
	s_barrier
	s_waitcnt lgkmcnt(0)
	s_setprio 1
	v_mfma_f32_16x16x32_bf16 v[110:113], v[192:195], v[146:149], v[110:113]
	ds_read_b128 v[208:211], v241 offset:16384
	v_mfma_f32_16x16x32_bf16 v[102:105], v[200:203], v[146:149], v[102:105]
	v_mfma_f32_16x16x32_bf16 v[94:97], v[192:195], v[154:157], v[94:97]
	ds_read_b128 v[212:215], v241 offset:17408
	v_mfma_f32_16x16x32_bf16 v[86:89], v[200:203], v[154:157], v[86:89]
	v_mfma_f32_16x16x32_bf16 v[78:81], v[192:195], v[176:179], v[78:81]
	ds_read_b128 v[216:219], v241 offset:18432
	v_mfma_f32_16x16x32_bf16 v[74:77], v[200:203], v[176:179], v[74:77]
	v_mfma_f32_16x16x32_bf16 v[70:73], v[192:195], v[184:187], v[70:73]
	ds_read_b128 v[220:223], v241 offset:19456
	v_mfma_f32_16x16x32_bf16 v[66:69], v[200:203], v[184:187], v[66:69]
	v_mfma_f32_16x16x32_bf16 v[110:113], v[196:199], v[150:153], v[110:113]
	ds_read_b128 v[224:227], v241 offset:20480
	v_mfma_f32_16x16x32_bf16 v[102:105], v[204:207], v[150:153], v[102:105]
	v_mfma_f32_16x16x32_bf16 v[94:97], v[196:199], v[158:161], v[94:97]
	ds_read_b128 v[228:231], v241 offset:21504
	v_mfma_f32_16x16x32_bf16 v[86:89], v[204:207], v[158:161], v[86:89]
	v_mfma_f32_16x16x32_bf16 v[78:81], v[196:199], v[180:183], v[78:81]
	ds_read_b128 v[232:235], v241 offset:22528
	v_mfma_f32_16x16x32_bf16 v[74:77], v[204:207], v[180:183], v[74:77]
	v_mfma_f32_16x16x32_bf16 v[70:73], v[196:199], v[188:191], v[70:73]
	ds_read_b128 v[246:249], v241 offset:23552
	v_mfma_f32_16x16x32_bf16 v[66:69], v[204:207], v[188:191], v[66:69]
	s_setprio 0
	s_barrier
	s_mov_b32 m0, s21
	s_add_u32 s94, s52, 0x80
	s_addc_u32 s95, s53, 0
	global_load_lds_dwordx4 v162, s[52:53]
	s_mov_b32 m0, s59
	s_nop 0
	global_load_lds_dwordx4 v164, s[52:53]
	s_waitcnt vmcnt(8)
	s_barrier
	s_waitcnt lgkmcnt(0)
	s_setprio 1
	v_mfma_f32_16x16x32_bf16 v[62:65], v[130:133], v[208:211], v[62:65]
	ds_read_b128 v[146:149], v241 offset:32768
	v_mfma_f32_16x16x32_bf16 v[58:61], v[138:141], v[208:211], v[58:61]
	v_mfma_f32_16x16x32_bf16 v[54:57], v[130:133], v[216:219], v[54:57]
	ds_read_b128 v[150:153], v241 offset:33792
	v_mfma_f32_16x16x32_bf16 v[50:53], v[138:141], v[216:219], v[50:53]
	v_mfma_f32_16x16x32_bf16 v[42:45], v[130:133], v[224:227], v[42:45]
	ds_read_b128 v[154:157], v241 offset:34816
	v_mfma_f32_16x16x32_bf16 v[34:37], v[138:141], v[224:227], v[34:37]
	v_mfma_f32_16x16x32_bf16 v[26:29], v[130:133], v[232:235], v[26:29]
	ds_read_b128 v[158:161], v241 offset:35840
	v_mfma_f32_16x16x32_bf16 v[18:21], v[138:141], v[232:235], v[18:21]
	v_mfma_f32_16x16x32_bf16 v[62:65], v[134:137], v[212:215], v[62:65]
	ds_read_b128 v[176:179], v241 offset:36864
	v_mfma_f32_16x16x32_bf16 v[58:61], v[142:145], v[212:215], v[58:61]
	v_mfma_f32_16x16x32_bf16 v[54:57], v[134:137], v[220:223], v[54:57]
	ds_read_b128 v[180:183], v241 offset:37888
	v_mfma_f32_16x16x32_bf16 v[50:53], v[142:145], v[220:223], v[50:53]
	v_mfma_f32_16x16x32_bf16 v[42:45], v[134:137], v[228:231], v[42:45]
	ds_read_b128 v[184:187], v241 offset:38912
	v_mfma_f32_16x16x32_bf16 v[34:37], v[142:145], v[228:231], v[34:37]
	v_mfma_f32_16x16x32_bf16 v[26:29], v[134:137], v[246:249], v[26:29]
	ds_read_b128 v[188:191], v241 offset:39936
	v_mfma_f32_16x16x32_bf16 v[18:21], v[142:145], v[246:249], v[18:21]
	s_setprio 0
	s_barrier
	s_add_u32 s82, s50, 0x80000
	s_addc_u32 s83, s51, 0
	s_add_i32 s81, s69, s56
	s_mov_b32 m0, s81
	s_nop 0
	global_load_lds_dwordx4 v162, s[82:83]
	s_add_i32 m0, s81, 0x2000
	s_nop 0
	global_load_lds_dwordx4 v164, s[82:83]
	s_waitcnt vmcnt(10)
	s_barrier
	s_waitcnt lgkmcnt(0)
	s_setprio 1
	v_mfma_f32_16x16x32_bf16 v[46:49], v[192:195], v[208:211], v[46:49]
	ds_read_b128 v[130:133], v168
	v_mfma_f32_16x16x32_bf16 v[38:41], v[200:203], v[208:211], v[38:41]
	v_mfma_f32_16x16x32_bf16 v[30:33], v[192:195], v[216:219], v[30:33]
	v_mfma_f32_16x16x32_bf16 v[22:25], v[200:203], v[216:219], v[22:25]
	v_mfma_f32_16x16x32_bf16 v[14:17], v[192:195], v[224:227], v[14:17]
	ds_read_b128 v[134:137], v168 offset:1024
	v_mfma_f32_16x16x32_bf16 v[10:13], v[200:203], v[224:227], v[10:13]
	v_mfma_f32_16x16x32_bf16 v[6:9], v[192:195], v[232:235], v[6:9]
	v_mfma_f32_16x16x32_bf16 v[2:5], v[200:203], v[232:235], v[2:5]
	v_mfma_f32_16x16x32_bf16 v[46:49], v[196:199], v[212:215], v[46:49]
	ds_read_b128 v[138:141], v168 offset:2048
	v_mfma_f32_16x16x32_bf16 v[38:41], v[204:207], v[212:215], v[38:41]
	v_mfma_f32_16x16x32_bf16 v[30:33], v[196:199], v[220:223], v[30:33]
	v_mfma_f32_16x16x32_bf16 v[22:25], v[204:207], v[220:223], v[22:25]
	v_mfma_f32_16x16x32_bf16 v[14:17], v[196:199], v[228:231], v[14:17]
	ds_read_b128 v[142:145], v168 offset:3072
	v_mfma_f32_16x16x32_bf16 v[10:13], v[204:207], v[228:231], v[10:13]
	v_mfma_f32_16x16x32_bf16 v[6:9], v[196:199], v[246:249], v[6:9]
	v_mfma_f32_16x16x32_bf16 v[2:5], v[204:207], v[246:249], v[2:5]
	s_setprio 0
	s_barrier
	s_add_i32 s81, 0, 0x18000
	s_add_u32 s52, s52, 0x80000
	s_addc_u32 s53, s53, 0
	s_mov_b32 m0, s60
	s_nop 0
	global_load_lds_dwordx4 v162, s[52:53]
	s_mov_b32 m0, s61
	s_nop 0
	global_load_lds_dwordx4 v164, s[52:53]
	s_waitcnt vmcnt(10)
	s_barrier
	s_waitcnt lgkmcnt(0)
	s_setprio 1
	v_mfma_f32_16x16x32_bf16 v[126:129], v[130:133], v[146:149], v[126:129]
	ds_read_b128 v[192:195], v169
	v_mfma_f32_16x16x32_bf16 v[122:125], v[138:141], v[146:149], v[122:125]
	v_mfma_f32_16x16x32_bf16 v[118:121], v[130:133], v[154:157], v[118:121]
	v_mfma_f32_16x16x32_bf16 v[114:117], v[138:141], v[154:157], v[114:117]
	v_mfma_f32_16x16x32_bf16 v[106:109], v[130:133], v[176:179], v[106:109]
	ds_read_b128 v[196:199], v169 offset:1024
	v_mfma_f32_16x16x32_bf16 v[98:101], v[138:141], v[176:179], v[98:101]
	v_mfma_f32_16x16x32_bf16 v[90:93], v[130:133], v[184:187], v[90:93]
	v_mfma_f32_16x16x32_bf16 v[82:85], v[138:141], v[184:187], v[82:85]
	v_mfma_f32_16x16x32_bf16 v[126:129], v[134:137], v[150:153], v[126:129]
	ds_read_b128 v[200:203], v169 offset:2048
	v_mfma_f32_16x16x32_bf16 v[122:125], v[142:145], v[150:153], v[122:125]
	v_mfma_f32_16x16x32_bf16 v[118:121], v[134:137], v[158:161], v[118:121]
	v_mfma_f32_16x16x32_bf16 v[114:117], v[142:145], v[158:161], v[114:117]
	v_mfma_f32_16x16x32_bf16 v[106:109], v[134:137], v[180:183], v[106:109]
	ds_read_b128 v[204:207], v169 offset:3072
	v_mfma_f32_16x16x32_bf16 v[98:101], v[142:145], v[180:183], v[98:101]
	v_mfma_f32_16x16x32_bf16 v[90:93], v[134:137], v[188:191], v[90:93]
	v_mfma_f32_16x16x32_bf16 v[82:85], v[142:145], v[188:191], v[82:85]
	s_setprio 0
	s_barrier
	s_add_i32 s52, 0, 0x1c000
	s_add_i32 s53, s81, s56
	s_mov_b32 m0, s53
	s_nop 0
	global_load_lds_dwordx4 v162, s[96:97]
	s_add_i32 m0, s53, 0x2000
	s_nop 0
	global_load_lds_dwordx4 v164, s[96:97]
	s_waitcnt vmcnt(10)
	s_barrier
	s_waitcnt lgkmcnt(0)
	s_setprio 1
	v_mfma_f32_16x16x32_bf16 v[110:113], v[192:195], v[146:149], v[110:113]
	ds_read_b128 v[208:211], v241 offset:49152
	v_mfma_f32_16x16x32_bf16 v[102:105], v[200:203], v[146:149], v[102:105]
	v_mfma_f32_16x16x32_bf16 v[94:97], v[192:195], v[154:157], v[94:97]
	ds_read_b128 v[212:215], v241 offset:50176
	v_mfma_f32_16x16x32_bf16 v[86:89], v[200:203], v[154:157], v[86:89]
	v_mfma_f32_16x16x32_bf16 v[78:81], v[192:195], v[176:179], v[78:81]
	ds_read_b128 v[216:219], v241 offset:51200
	v_mfma_f32_16x16x32_bf16 v[74:77], v[200:203], v[176:179], v[74:77]
	v_mfma_f32_16x16x32_bf16 v[70:73], v[192:195], v[184:187], v[70:73]
	ds_read_b128 v[220:223], v241 offset:52224
	v_mfma_f32_16x16x32_bf16 v[66:69], v[200:203], v[184:187], v[66:69]
	v_mfma_f32_16x16x32_bf16 v[110:113], v[196:199], v[150:153], v[110:113]
	ds_read_b128 v[224:227], v241 offset:53248
	v_mfma_f32_16x16x32_bf16 v[102:105], v[204:207], v[150:153], v[102:105]
	v_mfma_f32_16x16x32_bf16 v[94:97], v[196:199], v[158:161], v[94:97]
	ds_read_b128 v[228:231], v241 offset:54272
	v_mfma_f32_16x16x32_bf16 v[86:89], v[204:207], v[158:161], v[86:89]
	v_mfma_f32_16x16x32_bf16 v[78:81], v[196:199], v[180:183], v[78:81]
	ds_read_b128 v[232:235], v241 offset:55296
	v_mfma_f32_16x16x32_bf16 v[74:77], v[204:207], v[180:183], v[74:77]
	v_mfma_f32_16x16x32_bf16 v[70:73], v[196:199], v[188:191], v[70:73]
	ds_read_b128 v[246:249], v241 offset:56320
	v_mfma_f32_16x16x32_bf16 v[66:69], v[204:207], v[188:191], v[66:69]
	s_setprio 0
	s_barrier
	s_mov_b32 m0, s64
	s_nop 0
	global_load_lds_dwordx4 v162, s[94:95]
	s_mov_b32 m0, s65
	s_nop 0
	global_load_lds_dwordx4 v164, s[94:95]
	s_waitcnt vmcnt(8)
	s_barrier
	s_waitcnt lgkmcnt(0)
	s_setprio 1
	v_mfma_f32_16x16x32_bf16 v[62:65], v[130:133], v[208:211], v[62:65]
	ds_read_b128 v[146:149], v241
	v_mfma_f32_16x16x32_bf16 v[58:61], v[138:141], v[208:211], v[58:61]
	v_mfma_f32_16x16x32_bf16 v[54:57], v[130:133], v[216:219], v[54:57]
	ds_read_b128 v[150:153], v241 offset:1024
	v_mfma_f32_16x16x32_bf16 v[50:53], v[138:141], v[216:219], v[50:53]
	v_mfma_f32_16x16x32_bf16 v[42:45], v[130:133], v[224:227], v[42:45]
	ds_read_b128 v[154:157], v241 offset:2048
	v_mfma_f32_16x16x32_bf16 v[34:37], v[138:141], v[224:227], v[34:37]
	v_mfma_f32_16x16x32_bf16 v[26:29], v[130:133], v[232:235], v[26:29]
	ds_read_b128 v[158:161], v241 offset:3072
	v_mfma_f32_16x16x32_bf16 v[18:21], v[138:141], v[232:235], v[18:21]
	v_mfma_f32_16x16x32_bf16 v[62:65], v[134:137], v[212:215], v[62:65]
	ds_read_b128 v[176:179], v241 offset:4096
	v_mfma_f32_16x16x32_bf16 v[58:61], v[142:145], v[212:215], v[58:61]
	v_mfma_f32_16x16x32_bf16 v[54:57], v[134:137], v[220:223], v[54:57]
	ds_read_b128 v[180:183], v241 offset:5120
	v_mfma_f32_16x16x32_bf16 v[50:53], v[142:145], v[220:223], v[50:53]
	v_mfma_f32_16x16x32_bf16 v[42:45], v[134:137], v[228:231], v[42:45]
	ds_read_b128 v[184:187], v241 offset:6144
	v_mfma_f32_16x16x32_bf16 v[34:37], v[142:145], v[228:231], v[34:37]
	v_mfma_f32_16x16x32_bf16 v[26:29], v[134:137], v[246:249], v[26:29]
	ds_read_b128 v[188:191], v241 offset:7168
	v_mfma_f32_16x16x32_bf16 v[18:21], v[142:145], v[246:249], v[18:21]
	s_setprio 0
	s_barrier
	s_add_u32 s50, s50, 0x80080
	s_addc_u32 s51, s51, 0
	s_add_i32 s52, s52, s56
	s_mov_b32 m0, s52
	s_nop 0
	global_load_lds_dwordx4 v162, s[50:51]
	s_add_i32 m0, s52, 0x2000
	s_nop 0
	global_load_lds_dwordx4 v164, s[50:51]
	s_waitcnt vmcnt(10)
	s_barrier
	s_waitcnt lgkmcnt(0)
	s_setprio 1
	v_mfma_f32_16x16x32_bf16 v[46:49], v[192:195], v[208:211], v[46:49]
	ds_read_b128 v[130:133], v240
	v_mfma_f32_16x16x32_bf16 v[38:41], v[200:203], v[208:211], v[38:41]
	v_mfma_f32_16x16x32_bf16 v[30:33], v[192:195], v[216:219], v[30:33]
	v_mfma_f32_16x16x32_bf16 v[22:25], v[200:203], v[216:219], v[22:25]
	v_mfma_f32_16x16x32_bf16 v[14:17], v[192:195], v[224:227], v[14:17]
	ds_read_b128 v[134:137], v240 offset:1024
	v_mfma_f32_16x16x32_bf16 v[10:13], v[200:203], v[224:227], v[10:13]
	v_mfma_f32_16x16x32_bf16 v[6:9], v[192:195], v[232:235], v[6:9]
	v_mfma_f32_16x16x32_bf16 v[2:5], v[200:203], v[232:235], v[2:5]
	v_mfma_f32_16x16x32_bf16 v[46:49], v[196:199], v[212:215], v[46:49]
	ds_read_b128 v[138:141], v240 offset:2048
	v_mfma_f32_16x16x32_bf16 v[38:41], v[204:207], v[212:215], v[38:41]
	v_mfma_f32_16x16x32_bf16 v[30:33], v[196:199], v[220:223], v[30:33]
	v_mfma_f32_16x16x32_bf16 v[22:25], v[204:207], v[220:223], v[22:25]
	v_mfma_f32_16x16x32_bf16 v[14:17], v[196:199], v[228:231], v[14:17]
	ds_read_b128 v[142:145], v240 offset:3072
	v_mfma_f32_16x16x32_bf16 v[10:13], v[204:207], v[228:231], v[10:13]
	v_mfma_f32_16x16x32_bf16 v[6:9], v[196:199], v[246:249], v[6:9]
	v_mfma_f32_16x16x32_bf16 v[2:5], v[204:207], v[246:249], v[2:5]
	s_setprio 0
	s_add_i32 s80, s80, 2
	s_add_u32 s48, s48, 0x100
	s_addc_u32 s49, s49, 0
	s_add_u32 s74, s74, 0x100
	s_addc_u32 s75, s75, 0
	s_cmp_gt_u32 s80, s87
	s_barrier
	s_cbranch_scc0 .LBB0_1098
